# v64 + gemm96 (G2a/G3) cross-tile prefetch: chunk 0 of the next tile issued at the start of the epilogue
# speedup vs baseline: 1.0111x; 1.0052x over previous
.LBB1_76:
	s_and_b64 vcc, exec, s[30:31]
	s_cbranch_vccz .LBB1_92
	s_cmp_gt_i32 s26, 7
	s_mov_b64 s[30:31], -1
	s_cbranch_scc0 .LBB1_85
	s_mov_b32 s59, 0
	s_mov_b32 s2, 0
	s_branch .LBB1_80

.LBB1_80:
	v_readlane_b32 s4, v242, 0
	s_lshl_b32 s5, s2, 3
	s_and_b32 s6, s4, 7
	s_or_b32 s5, s6, s5
	s_mul_i32 s5, s5, s55
	s_ashr_i32 s4, s4, 3
	s_add_i32 s4, s5, s4
	s_cmpk_gt_i32 s4, 0x57f
	s_mov_b64 s[30:31], -1
	s_cbranch_scc1 .LBB1_79
	s_ashr_i32 s5, s4, 31
	s_lshr_b32 s5, s5, 26
	s_add_i32 s5, s4, s5
	s_lshr_b32 s6, s5, 3
	s_andn2_b32 s5, s5, 63
	s_sub_i32 s4, s4, s5
	s_ashr_i32 s5, s4, 31
	s_lshr_b32 s5, s5, 29
	s_add_i32 s7, s4, s5
	s_and_b32 s5, s7, 0x7fffff8
	s_and_b32 s6, s6, 0x1ffffff8
	s_sub_i32 s4, s4, s5
	v_mov_b32_e32 v90, v162
	s_add_i32 s5, s4, s6
	s_load_dwordx16 s[40:55], s[0:1], 0x140
	s_mulk_i32 s5, 0x60
	v_ashrrev_i32_e32 v44, 3, v90
	v_add_u32_e32 v0, s5, v44
	v_ashrrev_i32_e32 v1, 31, v0
	v_lshlrev_b64 v[0:1], 11, v[0:1]
	s_lshl_b32 s4, s7, 4
	s_waitcnt lgkmcnt(0)
	v_lshl_add_u64 v[0:1], s[50:51], 0, v[0:1]
	v_lshlrev_b32_e32 v2, 4, v90
	s_load_dwordx16 s[40:55], s[0:1], 0xc0
	s_and_b32 s4, s4, 0xffffff80
	v_and_b32_e32 v128, 0x70, v2
	v_lshl_add_u64 v[76:77], v[0:1], 0, v[128:129]
	v_add_u32_e32 v0, s4, v44
	v_ashrrev_i32_e32 v1, 31, v0
	v_lshlrev_b64 v[0:1], 11, v[0:1]
	s_waitcnt lgkmcnt(0)
	v_lshl_add_u64 v[0:1], s[50:51], 0, v[0:1]
	s_mov_b32 s6, 0x10000
	v_lshl_add_u64 v[78:79], v[0:1], 0, v[128:129]
	v_add_co_u32_e32 v0, vcc, s6, v76
	s_mov_b32 s7, 0x30000
	s_nop 0
	v_addc_co_u32_e32 v1, vcc, 0, v77, vcc
	v_add_co_u32_e32 v30, vcc, s6, v78
	s_mov_b32 s6, 0x20000
	s_nop 0
	v_addc_co_u32_e32 v31, vcc, 0, v79, vcc
	v_add_co_u32_e32 v32, vcc, s6, v78
	s_nop 0
	v_addc_co_u32_e32 v33, vcc, 0, v79, vcc
	v_add_co_u32_e32 v34, vcc, s7, v78
	s_nop 0
	v_addc_co_u32_e32 v35, vcc, 0, v79, vcc
	v_add_co_u32_e32 v36, vcc, s6, v76
	v_addc_co_u32_e32 v37, vcc, 0, v77, vcc
	s_barrier
	s_nop 0
	v_ashrrev_i32_e32 v1, 7, v90
	s_movk_i32 s8, 0x90
	v_and_b32_e32 v92, 15, v90
	v_mul_lo_u32 v31, v44, s8
	v_mul_lo_u32 v93, v1, 48
	v_bfe_u32 v91, v90, 4, 2
	v_and_b32_e32 v30, 0x4f, v90
	v_add3_u32 v94, v128, v31, 16
	v_or_b32_e32 v31, v93, v92
	v_mov_b32_e32 v0, 0
	v_lshl_add_u32 v1, v91, 4, 16
	v_mul_u32_u24_e32 v30, 0x90, v30
	v_mul_lo_u32 v31, v31, s8
	s_mov_b64 s[8:9], 0x10000
	s_mov_b64 s[10:11], 0x20000
	s_mov_b64 s[12:13], 0x30000
	s_mov_b32 s7, 0
	s_movk_i32 s6, 0x80
	v_add_u32_e32 v95, 0xd800, v94
	v_add_u32_e32 v96, v1, v31
	v_lshl_add_u64 v[80:81], v[78:79], 0, s[8:9]
	v_lshl_add_u64 v[82:83], v[78:79], 0, s[10:11]
	v_lshl_add_u64 v[84:85], v[78:79], 0, s[12:13]
	v_lshl_add_u64 v[86:87], v[76:77], 0, s[8:9]
	v_lshl_add_u64 v[88:89], v[76:77], 0, s[10:11]
	v_add_u32_e32 v97, v1, v30
	v_mov_b32_e32 v1, v0
	v_mov_b32_e32 v30, v0
	v_mov_b32_e32 v31, v0
	v_mov_b32_e32 v32, v0
	v_mov_b32_e32 v33, v0
	v_mov_b32_e32 v34, v0
	v_mov_b32_e32 v35, v0
	v_mov_b32_e32 v44, v0
	v_mov_b32_e32 v45, v0
	v_mov_b32_e32 v46, v0
	v_mov_b32_e32 v47, v0
	v_mov_b32_e32 v68, v0
	v_mov_b32_e32 v69, v0
	v_mov_b32_e32 v70, v0
	v_mov_b32_e32 v71, v0
	v_mov_b32_e32 v72, v0
	v_mov_b32_e32 v73, v0
	v_mov_b32_e32 v74, v0
	v_mov_b32_e32 v75, v0
	s_waitcnt vmcnt(12)
	s_waitcnt vmcnt(11)
	s_waitcnt vmcnt(10)
	s_waitcnt vmcnt(9)
	s_waitcnt vmcnt(8)
	s_waitcnt vmcnt(7)
	v_mov_b32_e32 v2, v0
	v_mov_b32_e32 v3, v0
	v_mov_b32_e32 v4, v0
	v_mov_b32_e32 v5, v0
	v_mov_b32_e32 v6, v0
	v_mov_b32_e32 v7, v0
	v_mov_b32_e32 v8, v0
	v_mov_b32_e32 v9, v0
	v_mov_b32_e32 v10, v0
	v_mov_b32_e32 v11, v0
	v_mov_b32_e32 v12, v0
	v_mov_b32_e32 v13, v0
	v_mov_b32_e32 v14, v0
	v_mov_b32_e32 v15, v0
	v_mov_b32_e32 v16, v0
	v_mov_b32_e32 v17, v0
	v_mov_b32_e32 v18, v0
	v_mov_b32_e32 v19, v0
	v_mov_b32_e32 v20, v0
	v_mov_b32_e32 v21, v0
	v_mov_b32_e32 v22, v0
	v_mov_b32_e32 v23, v0
	v_mov_b32_e32 v24, v0
	v_mov_b32_e32 v25, v0
	v_mov_b32_e32 v26, v0
	v_mov_b32_e32 v27, v0
	v_mov_b32_e32 v28, v0
	v_mov_b32_e32 v29, v0
	s_waitcnt lgkmcnt(0)
	s_barrier
	v_and_b32_e32 v204, 15, v168
	v_lshrrev_b32_e32 v205, 4, v168
	v_bfe_u32 v206, v168, 1, 3
	v_xor_b32_e32 v205, v205, v206
	v_lshlrev_b32_e32 v205, 4, v205
	v_readfirstlane_b32 s19, v162
	v_readfirstlane_b32 s8, v76
	v_readfirstlane_b32 s9, v77
	v_readfirstlane_b32 s10, v78
	v_readfirstlane_b32 s11, v79
	s_lshr_b32 s19, s19, 6
	s_lshr_b32 s16, s19, 1
	s_and_b32 s17, s19, 1
	s_mul_i32 s16, s16, 48
	v_add_u32_e32 v206, s16, v204
	v_lshl_add_u32 v232, v206, 7, v205
	v_xor_b32_e32 v233, 64, v232
	v_add_u32_e32 v232, 16, v232
	v_add_u32_e32 v233, 16, v233
	v_lshl_add_u32 v206, s17, 6, v204
	v_lshl_add_u32 v234, v206, 7, v205
	v_xor_b32_e32 v235, 64, v234
	v_add_u32_e32 v234, 0x3010, v234
	v_add_u32_e32 v235, 0x3010, v235
	v_lshrrev_b32_e32 v206, 3, v168
	v_and_b32_e32 v207, 7, v168
	v_lshrrev_b32_e32 v204, 1, v206
	v_xor_b32_e32 v207, v207, v204
	v_lshlrev_b32_e32 v207, 4, v207
	v_lshl_add_u32 v236, v206, 11, v207
	v_xor_b32_e32 v237, 64, v236
	s_and_b32 s17, s19, 1
	s_cmp_eq_u32 s17, 0
	s_cselect_b64 vcc, -1, 0
	s_nop 3
	v_cndmask_b32_e32 v238, v237, v236, vcc
	v_cndmask_b32_e32 v239, v236, v237, vcc
	s_mul_i32 s16, s19, 0x8000
	s_add_u32 s8, s8, s16
	s_addc_u32 s9, s9, 0
	s_mul_i32 s16, s19, 0xc000
	s_add_u32 s10, s10, s16
	s_addc_u32 s11, s11, 0
	s_mul_i32 s16, s19, 0xc00
	s_lshl_b32 s17, s19, 12
	s_cmp_eq_u32 s59, 1
	s_cbranch_scc1 .Lg96pf_skip_LBB1_82
	s_add_i32 m0, s16, 0x10
	s_nop 0
	global_load_lds_dwordx4 v238, s[8:9]
	s_add_i32 m0, s16, 0x410
	s_add_u32 s12, s8, 0x4000
	s_addc_u32 s13, s9, 0
	global_load_lds_dwordx4 v239, s[12:13]
	s_add_i32 m0, s16, 0x810
	s_add_u32 s12, s8, 0x8000
	s_addc_u32 s13, s9, 0
	global_load_lds_dwordx4 v238, s[12:13]
	s_add_i32 m0, s17, 0x3010
	s_nop 0
	global_load_lds_dwordx4 v236, s[10:11]
	s_add_i32 m0, s17, 0x3410
	s_add_u32 s12, s10, 0x4000
	s_addc_u32 s13, s11, 0
	global_load_lds_dwordx4 v237, s[12:13]
	s_add_i32 m0, s17, 0x3810
	s_add_u32 s12, s10, 0x8000
	s_addc_u32 s13, s11, 0
	global_load_lds_dwordx4 v236, s[12:13]
	s_add_i32 m0, s17, 0x3c10
	s_add_u32 s12, s10, 0xc000
	s_addc_u32 s13, s11, 0
	global_load_lds_dwordx4 v237, s[12:13]
.Lg96pf_skip_LBB1_82:
	s_mov_b32 s59, 0
	s_mov_b32 s18, 0
	s_waitcnt vmcnt(0)
	s_barrier
	s_setprio 1
.LBB1_82:
	s_lshl_b32 s19, s18, 8
	s_add_i32 s19, s19, 0x80
	s_min_u32 s19, s19, 0x780
	s_add_u32 s40, s8, s19
	s_addc_u32 s41, s9, 0
	s_add_u32 s42, s10, s19
	s_addc_u32 s43, s11, 0
	ds_read_b128 v[142:145], v234 offset:0
	ds_read_b128 v[146:149], v234 offset:2048
	ds_read_b128 v[150:153], v234 offset:4096
	ds_read_b128 v[154:157], v234 offset:6144
	ds_read_b128 v[130:133], v232 offset:0
	ds_read_b128 v[134:137], v232 offset:2048
	ds_read_b128 v[138:141], v232 offset:4096
	ds_read_b128 v[216:219], v235 offset:0
	ds_read_b128 v[220:223], v235 offset:2048
	ds_read_b128 v[224:227], v235 offset:4096
	ds_read_b128 v[228:231], v235 offset:6144
	ds_read_b128 v[188:191], v233 offset:0
	ds_read_b128 v[192:195], v233 offset:2048
	ds_read_b128 v[196:199], v233 offset:4096
	s_waitcnt lgkmcnt(9)
	s_add_i32 m0, s16, 0x7010
	s_nop 0
	v_mfma_f32_16x16x32_bf16 v[72:75], v[142:145], v[130:133], v[72:75]
	global_load_lds_dwordx4 v238, s[40:41]
	s_add_i32 m0, s16, 0x7410
	s_add_u32 s12, s40, 0x4000
	s_addc_u32 s13, s41, 0
	v_mfma_f32_16x16x32_bf16 v[68:71], v[146:149], v[130:133], v[68:71]
	global_load_lds_dwordx4 v239, s[12:13]
	v_mfma_f32_16x16x32_bf16 v[44:47], v[150:153], v[130:133], v[44:47]
	v_mfma_f32_16x16x32_bf16 v[32:35], v[154:157], v[130:133], v[32:35]
	s_waitcnt lgkmcnt(8)
	s_add_i32 m0, s16, 0x7810
	s_add_u32 s12, s40, 0x8000
	s_addc_u32 s13, s41, 0
	v_mfma_f32_16x16x32_bf16 v[28:31], v[142:145], v[134:137], v[28:31]
	v_mfma_f32_16x16x32_bf16 v[24:27], v[146:149], v[134:137], v[24:27]
	global_load_lds_dwordx4 v238, s[12:13]
	v_mfma_f32_16x16x32_bf16 v[20:23], v[150:153], v[134:137], v[20:23]
	v_mfma_f32_16x16x32_bf16 v[16:19], v[154:157], v[134:137], v[16:19]
	s_waitcnt lgkmcnt(7)
	s_add_i32 m0, s17, 0xa010
	s_nop 0
	v_mfma_f32_16x16x32_bf16 v[12:15], v[142:145], v[138:141], v[12:15]
	v_mfma_f32_16x16x32_bf16 v[8:11], v[146:149], v[138:141], v[8:11]
	global_load_lds_dwordx4 v236, s[42:43]
	v_mfma_f32_16x16x32_bf16 v[4:7], v[150:153], v[138:141], v[4:7]
	v_mfma_f32_16x16x32_bf16 v[0:3], v[154:157], v[138:141], v[0:3]
	s_waitcnt lgkmcnt(2)
	s_add_i32 m0, s17, 0xa410
	s_add_u32 s12, s42, 0x4000
	s_addc_u32 s13, s43, 0
	v_mfma_f32_16x16x32_bf16 v[72:75], v[216:219], v[188:191], v[72:75]
	v_mfma_f32_16x16x32_bf16 v[68:71], v[220:223], v[188:191], v[68:71]
	global_load_lds_dwordx4 v237, s[12:13]
	v_mfma_f32_16x16x32_bf16 v[44:47], v[224:227], v[188:191], v[44:47]
	v_mfma_f32_16x16x32_bf16 v[32:35], v[228:231], v[188:191], v[32:35]
	s_waitcnt lgkmcnt(1)
	s_add_i32 m0, s17, 0xa810
	s_add_u32 s12, s42, 0x8000
	s_addc_u32 s13, s43, 0
	v_mfma_f32_16x16x32_bf16 v[28:31], v[216:219], v[192:195], v[28:31]
	v_mfma_f32_16x16x32_bf16 v[24:27], v[220:223], v[192:195], v[24:27]
	global_load_lds_dwordx4 v236, s[12:13]
	v_mfma_f32_16x16x32_bf16 v[20:23], v[224:227], v[192:195], v[20:23]
	v_mfma_f32_16x16x32_bf16 v[16:19], v[228:231], v[192:195], v[16:19]
	s_waitcnt lgkmcnt(0)
	s_add_i32 m0, s17, 0xac10
	s_add_u32 s12, s42, 0xc000
	s_addc_u32 s13, s43, 0
	v_mfma_f32_16x16x32_bf16 v[12:15], v[216:219], v[196:199], v[12:15]
	v_mfma_f32_16x16x32_bf16 v[8:11], v[220:223], v[196:199], v[8:11]
	global_load_lds_dwordx4 v237, s[12:13]
	v_mfma_f32_16x16x32_bf16 v[4:7], v[224:227], v[196:199], v[4:7]
	v_mfma_f32_16x16x32_bf16 v[0:3], v[228:231], v[196:199], v[0:3]
	s_waitcnt vmcnt(0)
	s_barrier
	s_lshl_b32 s19, s18, 8
	s_add_i32 s19, s19, 0x100
	s_min_u32 s19, s19, 0x780
	s_add_u32 s40, s8, s19
	s_addc_u32 s41, s9, 0
	s_add_u32 s42, s10, s19
	s_addc_u32 s43, s11, 0
	ds_read_b128 v[142:145], v234 offset:28672
	ds_read_b128 v[146:149], v234 offset:30720
	ds_read_b128 v[150:153], v234 offset:32768
	ds_read_b128 v[154:157], v234 offset:34816
	ds_read_b128 v[130:133], v232 offset:28672
	ds_read_b128 v[134:137], v232 offset:30720
	ds_read_b128 v[138:141], v232 offset:32768
	ds_read_b128 v[216:219], v235 offset:28672
	ds_read_b128 v[220:223], v235 offset:30720
	ds_read_b128 v[224:227], v235 offset:32768
	ds_read_b128 v[228:231], v235 offset:34816
	ds_read_b128 v[188:191], v233 offset:28672
	ds_read_b128 v[192:195], v233 offset:30720
	ds_read_b128 v[196:199], v233 offset:32768
	s_waitcnt lgkmcnt(9)
	s_add_i32 m0, s16, 0x10
	s_nop 0
	v_mfma_f32_16x16x32_bf16 v[72:75], v[142:145], v[130:133], v[72:75]
	global_load_lds_dwordx4 v238, s[40:41]
	s_add_i32 m0, s16, 0x410
	s_add_u32 s12, s40, 0x4000
	s_addc_u32 s13, s41, 0
	v_mfma_f32_16x16x32_bf16 v[68:71], v[146:149], v[130:133], v[68:71]
	global_load_lds_dwordx4 v239, s[12:13]
	v_mfma_f32_16x16x32_bf16 v[44:47], v[150:153], v[130:133], v[44:47]
	v_mfma_f32_16x16x32_bf16 v[32:35], v[154:157], v[130:133], v[32:35]
	s_waitcnt lgkmcnt(8)
	s_add_i32 m0, s16, 0x810
	s_add_u32 s12, s40, 0x8000
	s_addc_u32 s13, s41, 0
	v_mfma_f32_16x16x32_bf16 v[28:31], v[142:145], v[134:137], v[28:31]
	v_mfma_f32_16x16x32_bf16 v[24:27], v[146:149], v[134:137], v[24:27]
	global_load_lds_dwordx4 v238, s[12:13]
	v_mfma_f32_16x16x32_bf16 v[20:23], v[150:153], v[134:137], v[20:23]
	v_mfma_f32_16x16x32_bf16 v[16:19], v[154:157], v[134:137], v[16:19]
	s_waitcnt lgkmcnt(7)
	s_add_i32 m0, s17, 0x3010
	s_nop 0
	v_mfma_f32_16x16x32_bf16 v[12:15], v[142:145], v[138:141], v[12:15]
	v_mfma_f32_16x16x32_bf16 v[8:11], v[146:149], v[138:141], v[8:11]
	global_load_lds_dwordx4 v236, s[42:43]
	v_mfma_f32_16x16x32_bf16 v[4:7], v[150:153], v[138:141], v[4:7]
	v_mfma_f32_16x16x32_bf16 v[0:3], v[154:157], v[138:141], v[0:3]
	s_waitcnt lgkmcnt(2)
	s_add_i32 m0, s17, 0x3410
	s_add_u32 s12, s42, 0x4000
	s_addc_u32 s13, s43, 0
	v_mfma_f32_16x16x32_bf16 v[72:75], v[216:219], v[188:191], v[72:75]
	v_mfma_f32_16x16x32_bf16 v[68:71], v[220:223], v[188:191], v[68:71]
	global_load_lds_dwordx4 v237, s[12:13]
	v_mfma_f32_16x16x32_bf16 v[44:47], v[224:227], v[188:191], v[44:47]
	v_mfma_f32_16x16x32_bf16 v[32:35], v[228:231], v[188:191], v[32:35]
	s_waitcnt lgkmcnt(1)
	s_add_i32 m0, s17, 0x3810
	s_add_u32 s12, s42, 0x8000
	s_addc_u32 s13, s43, 0
	v_mfma_f32_16x16x32_bf16 v[28:31], v[216:219], v[192:195], v[28:31]
	v_mfma_f32_16x16x32_bf16 v[24:27], v[220:223], v[192:195], v[24:27]
	global_load_lds_dwordx4 v236, s[12:13]
	v_mfma_f32_16x16x32_bf16 v[20:23], v[224:227], v[192:195], v[20:23]
	v_mfma_f32_16x16x32_bf16 v[16:19], v[228:231], v[192:195], v[16:19]
	s_waitcnt lgkmcnt(0)
	s_add_i32 m0, s17, 0x3c10
	s_add_u32 s12, s42, 0xc000
	s_addc_u32 s13, s43, 0
	v_mfma_f32_16x16x32_bf16 v[12:15], v[216:219], v[196:199], v[12:15]
	v_mfma_f32_16x16x32_bf16 v[8:11], v[220:223], v[196:199], v[8:11]
	global_load_lds_dwordx4 v237, s[12:13]
	v_mfma_f32_16x16x32_bf16 v[4:7], v[224:227], v[196:199], v[4:7]
	v_mfma_f32_16x16x32_bf16 v[0:3], v[228:231], v[196:199], v[0:3]
	s_waitcnt vmcnt(0)
	s_barrier
	s_add_i32 s18, s18, 1
	s_cmp_eq_u32 s18, 8
	s_cbranch_scc0 .LBB1_82
	s_setprio 0
	s_waitcnt vmcnt(0)
	v_readlane_b32 s14, v242, 0
	s_add_i32 s15, s2, 1
	s_lshl_b32 s15, s15, 3
	s_and_b32 s24, s14, 7
	s_or_b32 s15, s15, s24
	s_mul_i32 s15, s15, s55
	s_lshr_b32 s14, s14, 3
	s_add_i32 s15, s15, s14
	s_cmp_lt_u32 s15, 0x580
	s_cselect_b32 s59, 1, 0
	s_cbranch_scc0 .Lg96pf_none_g3
	s_lshr_b32 s14, s15, 6
	s_lshl_b32 s14, s14, 3
	s_and_b32 s24, s15, 7
	s_add_i32 s14, s14, s24
	s_mul_i32 s14, s14, 96
	s_sub_i32 s14, s14, s5
	s_bfe_u32 s24, s15, 0x30003
	s_lshl_b32 s24, s24, 7
	s_sub_i32 s24, s24, s4
	s_ashr_i32 s15, s14, 31
	s_lshl_b64 s[14:15], s[14:15], 11
	s_add_u32 s88, s8, s14
	s_addc_u32 s89, s9, s15
	s_ashr_i32 s25, s24, 31
	s_lshl_b64 s[24:25], s[24:25], 11
	s_add_u32 s90, s10, s24
	s_addc_u32 s91, s11, s25
	s_add_i32 m0, s16, 0x10
	s_nop 0
	global_load_lds_dwordx4 v238, s[88:89]
	s_add_i32 m0, s16, 0x410
	s_add_u32 s14, s88, 0x4000
	s_addc_u32 s15, s89, 0
	global_load_lds_dwordx4 v239, s[14:15]
	s_add_i32 m0, s16, 0x810
	s_add_u32 s14, s88, 0x8000
	s_addc_u32 s15, s89, 0
	global_load_lds_dwordx4 v238, s[14:15]
	s_add_i32 m0, s17, 0x3010
	s_nop 0
	global_load_lds_dwordx4 v236, s[90:91]
	s_add_i32 m0, s17, 0x3410
	s_add_u32 s14, s90, 0x4000
	s_addc_u32 s15, s91, 0
	global_load_lds_dwordx4 v237, s[14:15]
	s_add_i32 m0, s17, 0x3810
	s_add_u32 s14, s90, 0x8000
	s_addc_u32 s15, s91, 0
	global_load_lds_dwordx4 v236, s[14:15]
	s_add_i32 m0, s17, 0x3c10
	s_add_u32 s14, s90, 0xc000
	s_addc_u32 s15, s91, 0
	global_load_lds_dwordx4 v237, s[14:15]
.Lg96pf_none_g3:
	v_readlane_b32 s10, v241, 32
	v_readlane_b32 s11, v241, 33
	v_and_b32_e32 v36, 15, v162
	v_bfe_u32 v37, v162, 4, 2
	v_lshrrev_b32_e32 v38, 7, v162
	v_and_b32_e32 v39, 64, v162
	v_mul_u32_u24_e32 v38, 48, v38
	v_add3_u32 v40, v38, v36, s5
	v_lshl_or_b32 v41, v37, 2, v39
	v_add_u32_e32 v41, s4, v41
	v_lshlrev_b32_e32 v41, 2, v41
	s_movk_i32 s8, 0x1fff
	s_movk_i32 s9, 0x3fff
	s_add_u32 s10, s10, 0x2000
	s_addc_u32 s11, s11, 0
	s_mov_b32 s6, 0x3fd744fd
	v_mov_b32_e32 v42, v40
	v_cmp_lt_u32_e32 vcc, s9, v42
	v_lshl_add_u32 v64, v42, 12, v41
	s_nop 0
	v_cndmask_b32_e32 v43, v177, v176, vcc
	v_cmp_lt_u32_e32 vcc, s8, v42
	s_nop 1
	v_cndmask_b32_e32 v43, 0, v43, vcc
	v_lshl_add_u32 v124, v43, 2, v41
	v_add_u32_e32 v42, 16, v40
	v_cmp_lt_u32_e32 vcc, s9, v42
	v_lshl_add_u32 v65, v42, 12, v41
	s_nop 0
	v_cndmask_b32_e32 v43, v177, v176, vcc
	v_cmp_lt_u32_e32 vcc, s8, v42
	s_nop 1
	v_cndmask_b32_e32 v43, 0, v43, vcc
	v_lshl_add_u32 v125, v43, 2, v41
	v_add_u32_e32 v42, 32, v40
	v_cmp_lt_u32_e32 vcc, s9, v42
	v_lshl_add_u32 v66, v42, 12, v41
	s_nop 0
	v_cndmask_b32_e32 v43, v177, v176, vcc
	v_cmp_lt_u32_e32 vcc, s8, v42
	s_nop 1
	v_cndmask_b32_e32 v43, 0, v43, vcc
	v_lshl_add_u32 v126, v43, 2, v41
	global_load_dwordx4 v[130:133], v124, s[10:11] offset:0
	global_load_dwordx4 v[76:79], v64, s[70:71] offset:0
	global_load_dwordx4 v[134:137], v124, s[10:11] offset:64
	global_load_dwordx4 v[80:83], v64, s[70:71] offset:64
	global_load_dwordx4 v[138:141], v124, s[10:11] offset:128
	global_load_dwordx4 v[84:87], v64, s[70:71] offset:128
	global_load_dwordx4 v[142:145], v124, s[10:11] offset:192
	global_load_dwordx4 v[88:91], v64, s[70:71] offset:192
	global_load_dwordx4 v[146:149], v125, s[10:11] offset:0
	global_load_dwordx4 v[92:95], v65, s[70:71] offset:0
	global_load_dwordx4 v[150:153], v125, s[10:11] offset:64
	global_load_dwordx4 v[96:99], v65, s[70:71] offset:64
	global_load_dwordx4 v[154:157], v125, s[10:11] offset:128
	global_load_dwordx4 v[100:103], v65, s[70:71] offset:128
	global_load_dwordx4 v[158:161], v125, s[10:11] offset:192
	global_load_dwordx4 v[104:107], v65, s[70:71] offset:192
	global_load_dwordx4 v[48:51], v126, s[10:11] offset:0
	global_load_dwordx4 v[108:111], v66, s[70:71] offset:0
	global_load_dwordx4 v[52:55], v126, s[10:11] offset:64
	global_load_dwordx4 v[112:115], v66, s[70:71] offset:64
	global_load_dwordx4 v[56:59], v126, s[10:11] offset:128
	global_load_dwordx4 v[116:119], v66, s[70:71] offset:128
	global_load_dwordx4 v[60:63], v126, s[10:11] offset:192
	global_load_dwordx4 v[120:123], v66, s[70:71] offset:192
	s_add_i32 s2, s2, 1
	v_readlane_b32 s55, v241, 23
	s_waitcnt vmcnt(22)
	v_pk_mul_f32 v[130:131], v[72:73], v[130:131]
	v_pk_mul_f32 v[132:133], v[74:75], v[132:133]
	v_pk_fma_f32 v[76:77], v[76:77], s[6:7], v[130:131] op_sel_hi:[1,0,1]
	v_pk_fma_f32 v[78:79], v[78:79], s[6:7], v[132:133] op_sel_hi:[1,0,1]
	global_store_dwordx4 v64, v[76:79], s[72:73] offset:0
	s_waitcnt vmcnt(20)
	v_pk_mul_f32 v[134:135], v[68:69], v[134:135]
	v_pk_mul_f32 v[136:137], v[70:71], v[136:137]
	v_pk_fma_f32 v[80:81], v[80:81], s[6:7], v[134:135] op_sel_hi:[1,0,1]
	v_pk_fma_f32 v[82:83], v[82:83], s[6:7], v[136:137] op_sel_hi:[1,0,1]
	global_store_dwordx4 v64, v[80:83], s[72:73] offset:64
	s_waitcnt vmcnt(18)
	v_pk_mul_f32 v[138:139], v[44:45], v[138:139]
	v_pk_mul_f32 v[140:141], v[46:47], v[140:141]
	v_pk_fma_f32 v[84:85], v[84:85], s[6:7], v[138:139] op_sel_hi:[1,0,1]
	v_pk_fma_f32 v[86:87], v[86:87], s[6:7], v[140:141] op_sel_hi:[1,0,1]
	global_store_dwordx4 v64, v[84:87], s[72:73] offset:128
	s_waitcnt vmcnt(16)
	v_pk_mul_f32 v[142:143], v[32:33], v[142:143]
	v_pk_mul_f32 v[144:145], v[34:35], v[144:145]
	v_pk_fma_f32 v[88:89], v[88:89], s[6:7], v[142:143] op_sel_hi:[1,0,1]
	v_pk_fma_f32 v[90:91], v[90:91], s[6:7], v[144:145] op_sel_hi:[1,0,1]
	global_store_dwordx4 v64, v[88:91], s[72:73] offset:192
	s_waitcnt vmcnt(14)
	v_pk_mul_f32 v[146:147], v[28:29], v[146:147]
	v_pk_mul_f32 v[148:149], v[30:31], v[148:149]
	v_pk_fma_f32 v[92:93], v[92:93], s[6:7], v[146:147] op_sel_hi:[1,0,1]
	v_pk_fma_f32 v[94:95], v[94:95], s[6:7], v[148:149] op_sel_hi:[1,0,1]
	global_store_dwordx4 v65, v[92:95], s[72:73] offset:0
	s_waitcnt vmcnt(12)
	v_pk_mul_f32 v[150:151], v[24:25], v[150:151]
	v_pk_mul_f32 v[152:153], v[26:27], v[152:153]
	v_pk_fma_f32 v[96:97], v[96:97], s[6:7], v[150:151] op_sel_hi:[1,0,1]
	v_pk_fma_f32 v[98:99], v[98:99], s[6:7], v[152:153] op_sel_hi:[1,0,1]
	global_store_dwordx4 v65, v[96:99], s[72:73] offset:64
	s_waitcnt vmcnt(10)
	v_pk_mul_f32 v[154:155], v[20:21], v[154:155]
	v_pk_mul_f32 v[156:157], v[22:23], v[156:157]
	v_pk_fma_f32 v[100:101], v[100:101], s[6:7], v[154:155] op_sel_hi:[1,0,1]
	v_pk_fma_f32 v[102:103], v[102:103], s[6:7], v[156:157] op_sel_hi:[1,0,1]
	global_store_dwordx4 v65, v[100:103], s[72:73] offset:128
	s_waitcnt vmcnt(8)
	v_pk_mul_f32 v[158:159], v[16:17], v[158:159]
	v_pk_mul_f32 v[160:161], v[18:19], v[160:161]
	v_pk_fma_f32 v[104:105], v[104:105], s[6:7], v[158:159] op_sel_hi:[1,0,1]
	v_pk_fma_f32 v[106:107], v[106:107], s[6:7], v[160:161] op_sel_hi:[1,0,1]
	global_store_dwordx4 v65, v[104:107], s[72:73] offset:192
	s_waitcnt vmcnt(6)
	v_pk_mul_f32 v[48:49], v[12:13], v[48:49]
	v_pk_mul_f32 v[50:51], v[14:15], v[50:51]
	v_pk_fma_f32 v[108:109], v[108:109], s[6:7], v[48:49] op_sel_hi:[1,0,1]
	v_pk_fma_f32 v[110:111], v[110:111], s[6:7], v[50:51] op_sel_hi:[1,0,1]
	global_store_dwordx4 v66, v[108:111], s[72:73] offset:0
	s_waitcnt vmcnt(4)
	v_pk_mul_f32 v[52:53], v[8:9], v[52:53]
	v_pk_mul_f32 v[54:55], v[10:11], v[54:55]
	v_pk_fma_f32 v[112:113], v[112:113], s[6:7], v[52:53] op_sel_hi:[1,0,1]
	v_pk_fma_f32 v[114:115], v[114:115], s[6:7], v[54:55] op_sel_hi:[1,0,1]
	global_store_dwordx4 v66, v[112:115], s[72:73] offset:64
	s_waitcnt vmcnt(2)
	v_pk_mul_f32 v[56:57], v[4:5], v[56:57]
	v_pk_mul_f32 v[58:59], v[6:7], v[58:59]
	v_pk_fma_f32 v[116:117], v[116:117], s[6:7], v[56:57] op_sel_hi:[1,0,1]
	v_pk_fma_f32 v[118:119], v[118:119], s[6:7], v[58:59] op_sel_hi:[1,0,1]
	global_store_dwordx4 v66, v[116:119], s[72:73] offset:128
	s_waitcnt vmcnt(0)
	v_pk_mul_f32 v[60:61], v[0:1], v[60:61]
	v_pk_mul_f32 v[62:63], v[2:3], v[62:63]
	v_pk_fma_f32 v[120:121], v[120:121], s[6:7], v[60:61] op_sel_hi:[1,0,1]
	v_pk_fma_f32 v[122:123], v[122:123], s[6:7], v[62:63] op_sel_hi:[1,0,1]
	global_store_dwordx4 v66, v[120:123], s[72:73] offset:192
	s_mov_b64 s[30:31], 0
	s_branch .LBB1_79

.LBB1_85:
	s_and_b64 vcc, exec, s[30:31]
	s_cbranch_vccz .LBB1_92
	s_mov_b32 s59, 0
	s_mov_b32 s2, 0
	s_branch .LBB1_88

.LBB1_88:
	v_readlane_b32 s4, v242, 0
	s_lshl_b32 s5, s2, 3
	s_and_b32 s6, s4, 7
	s_or_b32 s5, s6, s5
	s_mul_i32 s5, s5, s55
	s_ashr_i32 s4, s4, 3
	s_add_i32 s4, s5, s4
	s_cmpk_gt_i32 s4, 0x57f
	s_mov_b64 s[30:31], -1
	s_cbranch_scc1 .LBB1_87
	s_ashr_i32 s5, s4, 31
	s_lshr_b32 s5, s5, 26
	s_add_i32 s5, s4, s5
	s_lshr_b32 s6, s5, 3
	s_andn2_b32 s5, s5, 63
	s_sub_i32 s4, s4, s5
	s_ashr_i32 s5, s4, 31
	s_lshr_b32 s5, s5, 29
	s_add_i32 s7, s4, s5
	s_and_b32 s5, s7, 0x7fffff8
	s_and_b32 s6, s6, 0x1ffffff8
	s_sub_i32 s4, s4, s5
	v_mov_b32_e32 v90, v162
	s_add_i32 s5, s4, s6
	s_load_dwordx16 s[40:55], s[0:1], 0x140
	s_mulk_i32 s5, 0x60
	v_ashrrev_i32_e32 v38, 3, v90
	v_add_u32_e32 v0, s5, v38
	v_ashrrev_i32_e32 v1, 31, v0
	v_lshlrev_b64 v[0:1], 11, v[0:1]
	s_lshl_b32 s4, s7, 4
	s_waitcnt lgkmcnt(0)
	v_lshl_add_u64 v[0:1], s[46:47], 0, v[0:1]
	v_lshlrev_b32_e32 v2, 4, v90
	s_load_dwordx16 s[40:55], s[0:1], 0xc0
	s_and_b32 s4, s4, 0xffffff80
	v_and_b32_e32 v128, 0x70, v2
	v_lshl_add_u64 v[76:77], v[0:1], 0, v[128:129]
	v_add_u32_e32 v0, s4, v38
	v_ashrrev_i32_e32 v1, 31, v0
	v_lshlrev_b64 v[0:1], 11, v[0:1]
	s_waitcnt lgkmcnt(0)
	v_lshl_add_u64 v[0:1], s[46:47], 0, v[0:1]
	s_mov_b32 s6, 0x10000
	v_lshl_add_u64 v[78:79], v[0:1], 0, v[128:129]
	v_add_co_u32_e32 v0, vcc, s6, v76
	s_mov_b32 s7, 0x30000
	s_nop 0
	v_addc_co_u32_e32 v1, vcc, 0, v77, vcc
	v_add_co_u32_e32 v30, vcc, s6, v78
	s_mov_b32 s6, 0x20000
	s_nop 0
	v_addc_co_u32_e32 v31, vcc, 0, v79, vcc
	v_add_co_u32_e32 v32, vcc, s6, v78
	s_nop 0
	v_addc_co_u32_e32 v33, vcc, 0, v79, vcc
	v_add_co_u32_e32 v34, vcc, s7, v78
	s_nop 0
	v_addc_co_u32_e32 v35, vcc, 0, v79, vcc
	v_add_co_u32_e32 v36, vcc, s6, v76
	v_addc_co_u32_e32 v37, vcc, 0, v77, vcc
	s_barrier
	v_ashrrev_i32_e32 v1, 7, v90
	s_movk_i32 s8, 0x90
	v_and_b32_e32 v92, 15, v90
	v_mul_lo_u32 v31, v38, s8
	v_mul_lo_u32 v93, v1, 48
	v_bfe_u32 v91, v90, 4, 2
	v_and_b32_e32 v30, 0x4f, v90
	v_add3_u32 v94, v128, v31, 16
	v_or_b32_e32 v31, v93, v92
	v_mov_b32_e32 v0, 0
	v_lshl_add_u32 v1, v91, 4, 16
	v_mul_u32_u24_e32 v30, 0x90, v30
	v_mul_lo_u32 v31, v31, s8
	s_mov_b64 s[8:9], 0x10000
	s_mov_b64 s[10:11], 0x20000
	s_mov_b64 s[12:13], 0x30000
	s_mov_b32 s7, 0
	s_movk_i32 s6, 0x80
	v_add_u32_e32 v95, 0xd800, v94
	v_add_u32_e32 v96, v1, v31
	v_lshl_add_u64 v[80:81], v[78:79], 0, s[8:9]
	v_lshl_add_u64 v[82:83], v[78:79], 0, s[10:11]
	v_lshl_add_u64 v[84:85], v[78:79], 0, s[12:13]
	v_lshl_add_u64 v[86:87], v[76:77], 0, s[8:9]
	v_lshl_add_u64 v[88:89], v[76:77], 0, s[10:11]
	v_add_u32_e32 v97, v1, v30
	v_mov_b32_e32 v1, v0
	v_mov_b32_e32 v30, v0
	v_mov_b32_e32 v31, v0
	v_mov_b32_e32 v32, v0
	v_mov_b32_e32 v33, v0
	v_mov_b32_e32 v34, v0
	v_mov_b32_e32 v35, v0
	v_mov_b32_e32 v36, v0
	v_mov_b32_e32 v37, v0
	v_mov_b32_e32 v38, v0
	v_mov_b32_e32 v39, v0
	v_mov_b32_e32 v40, v0
	v_mov_b32_e32 v41, v0
	v_mov_b32_e32 v42, v0
	v_mov_b32_e32 v43, v0
	v_mov_b32_e32 v72, v0
	v_mov_b32_e32 v73, v0
	v_mov_b32_e32 v74, v0
	v_mov_b32_e32 v75, v0
	s_waitcnt vmcnt(12)
	s_waitcnt vmcnt(11)
	s_waitcnt vmcnt(10)
	s_waitcnt vmcnt(9)
	s_waitcnt vmcnt(8)
	s_waitcnt vmcnt(7)
	v_mov_b32_e32 v2, v0
	v_mov_b32_e32 v3, v0
	v_mov_b32_e32 v4, v0
	v_mov_b32_e32 v5, v0
	v_mov_b32_e32 v6, v0
	v_mov_b32_e32 v7, v0
	v_mov_b32_e32 v8, v0
	v_mov_b32_e32 v9, v0
	v_mov_b32_e32 v10, v0
	v_mov_b32_e32 v11, v0
	v_mov_b32_e32 v12, v0
	v_mov_b32_e32 v13, v0
	v_mov_b32_e32 v14, v0
	v_mov_b32_e32 v15, v0
	v_mov_b32_e32 v16, v0
	v_mov_b32_e32 v17, v0
	v_mov_b32_e32 v18, v0
	v_mov_b32_e32 v19, v0
	v_mov_b32_e32 v20, v0
	v_mov_b32_e32 v21, v0
	v_mov_b32_e32 v22, v0
	v_mov_b32_e32 v23, v0
	v_mov_b32_e32 v24, v0
	v_mov_b32_e32 v25, v0
	v_mov_b32_e32 v26, v0
	v_mov_b32_e32 v27, v0
	v_mov_b32_e32 v28, v0
	v_mov_b32_e32 v29, v0
	s_waitcnt lgkmcnt(0)
	s_barrier
	v_and_b32_e32 v204, 15, v168
	v_lshrrev_b32_e32 v205, 4, v168
	v_bfe_u32 v206, v168, 1, 3
	v_xor_b32_e32 v205, v205, v206
	v_lshlrev_b32_e32 v205, 4, v205
	v_readfirstlane_b32 s19, v162
	v_readfirstlane_b32 s8, v76
	v_readfirstlane_b32 s9, v77
	v_readfirstlane_b32 s10, v78
	v_readfirstlane_b32 s11, v79
	s_lshr_b32 s19, s19, 6
	s_lshr_b32 s16, s19, 1
	s_and_b32 s17, s19, 1
	s_mul_i32 s16, s16, 48
	v_add_u32_e32 v206, s16, v204
	v_lshl_add_u32 v232, v206, 7, v205
	v_xor_b32_e32 v233, 64, v232
	v_add_u32_e32 v232, 16, v232
	v_add_u32_e32 v233, 16, v233
	v_lshl_add_u32 v206, s17, 6, v204
	v_lshl_add_u32 v234, v206, 7, v205
	v_xor_b32_e32 v235, 64, v234
	v_add_u32_e32 v234, 0x3010, v234
	v_add_u32_e32 v235, 0x3010, v235
	v_lshrrev_b32_e32 v206, 3, v168
	v_and_b32_e32 v207, 7, v168
	v_lshrrev_b32_e32 v204, 1, v206
	v_xor_b32_e32 v207, v207, v204
	v_lshlrev_b32_e32 v207, 4, v207
	v_lshl_add_u32 v236, v206, 11, v207
	v_xor_b32_e32 v237, 64, v236
	s_and_b32 s17, s19, 1
	s_cmp_eq_u32 s17, 0
	s_cselect_b64 vcc, -1, 0
	s_nop 3
	v_cndmask_b32_e32 v238, v237, v236, vcc
	v_cndmask_b32_e32 v239, v236, v237, vcc
	s_mul_i32 s16, s19, 0x8000
	s_add_u32 s8, s8, s16
	s_addc_u32 s9, s9, 0
	s_mul_i32 s16, s19, 0xc000
	s_add_u32 s10, s10, s16
	s_addc_u32 s11, s11, 0
	s_mul_i32 s16, s19, 0xc00
	s_lshl_b32 s17, s19, 12
	s_cmp_eq_u32 s59, 1
	s_cbranch_scc1 .Lg96pf_skip_LBB1_90
	s_add_i32 m0, s16, 0x10
	s_nop 0
	global_load_lds_dwordx4 v238, s[8:9]
	s_add_i32 m0, s16, 0x410
	s_add_u32 s12, s8, 0x4000
	s_addc_u32 s13, s9, 0
	global_load_lds_dwordx4 v239, s[12:13]
	s_add_i32 m0, s16, 0x810
	s_add_u32 s12, s8, 0x8000
	s_addc_u32 s13, s9, 0
	global_load_lds_dwordx4 v238, s[12:13]
	s_add_i32 m0, s17, 0x3010
	s_nop 0
	global_load_lds_dwordx4 v236, s[10:11]
	s_add_i32 m0, s17, 0x3410
	s_add_u32 s12, s10, 0x4000
	s_addc_u32 s13, s11, 0
	global_load_lds_dwordx4 v237, s[12:13]
	s_add_i32 m0, s17, 0x3810
	s_add_u32 s12, s10, 0x8000
	s_addc_u32 s13, s11, 0
	global_load_lds_dwordx4 v236, s[12:13]
	s_add_i32 m0, s17, 0x3c10
	s_add_u32 s12, s10, 0xc000
	s_addc_u32 s13, s11, 0
	global_load_lds_dwordx4 v237, s[12:13]

.LBB1_90:
	s_lshl_b32 s19, s18, 8
	s_add_i32 s19, s19, 0x80
	s_min_u32 s19, s19, 0x780
	s_add_u32 s40, s8, s19
	s_addc_u32 s41, s9, 0
	s_add_u32 s42, s10, s19
	s_addc_u32 s43, s11, 0
	ds_read_b128 v[142:145], v234 offset:0
	ds_read_b128 v[146:149], v234 offset:2048
	ds_read_b128 v[150:153], v234 offset:4096
	ds_read_b128 v[154:157], v234 offset:6144
	ds_read_b128 v[130:133], v232 offset:0
	ds_read_b128 v[134:137], v232 offset:2048
	ds_read_b128 v[138:141], v232 offset:4096
	ds_read_b128 v[216:219], v235 offset:0
	ds_read_b128 v[220:223], v235 offset:2048
	ds_read_b128 v[224:227], v235 offset:4096
	ds_read_b128 v[228:231], v235 offset:6144
	ds_read_b128 v[188:191], v233 offset:0
	ds_read_b128 v[192:195], v233 offset:2048
	ds_read_b128 v[196:199], v233 offset:4096
	s_waitcnt lgkmcnt(9)
	s_add_i32 m0, s16, 0x7010
	s_nop 0
	v_mfma_f32_16x16x32_bf16 v[72:75], v[142:145], v[130:133], v[72:75]
	global_load_lds_dwordx4 v238, s[40:41]
	s_add_i32 m0, s16, 0x7410
	s_add_u32 s12, s40, 0x4000
	s_addc_u32 s13, s41, 0
	v_mfma_f32_16x16x32_bf16 v[40:43], v[146:149], v[130:133], v[40:43]
	global_load_lds_dwordx4 v239, s[12:13]
	v_mfma_f32_16x16x32_bf16 v[36:39], v[150:153], v[130:133], v[36:39]
	v_mfma_f32_16x16x32_bf16 v[32:35], v[154:157], v[130:133], v[32:35]
	s_waitcnt lgkmcnt(8)
	s_add_i32 m0, s16, 0x7810
	s_add_u32 s12, s40, 0x8000
	s_addc_u32 s13, s41, 0
	v_mfma_f32_16x16x32_bf16 v[28:31], v[142:145], v[134:137], v[28:31]
	v_mfma_f32_16x16x32_bf16 v[24:27], v[146:149], v[134:137], v[24:27]
	global_load_lds_dwordx4 v238, s[12:13]
	v_mfma_f32_16x16x32_bf16 v[20:23], v[150:153], v[134:137], v[20:23]
	v_mfma_f32_16x16x32_bf16 v[16:19], v[154:157], v[134:137], v[16:19]
	s_waitcnt lgkmcnt(7)
	s_add_i32 m0, s17, 0xa010
	s_nop 0
	v_mfma_f32_16x16x32_bf16 v[12:15], v[142:145], v[138:141], v[12:15]
	v_mfma_f32_16x16x32_bf16 v[8:11], v[146:149], v[138:141], v[8:11]
	global_load_lds_dwordx4 v236, s[42:43]
	v_mfma_f32_16x16x32_bf16 v[4:7], v[150:153], v[138:141], v[4:7]
	v_mfma_f32_16x16x32_bf16 v[0:3], v[154:157], v[138:141], v[0:3]
	s_waitcnt lgkmcnt(2)
	s_add_i32 m0, s17, 0xa410
	s_add_u32 s12, s42, 0x4000
	s_addc_u32 s13, s43, 0
	v_mfma_f32_16x16x32_bf16 v[72:75], v[216:219], v[188:191], v[72:75]
	v_mfma_f32_16x16x32_bf16 v[40:43], v[220:223], v[188:191], v[40:43]
	global_load_lds_dwordx4 v237, s[12:13]
	v_mfma_f32_16x16x32_bf16 v[36:39], v[224:227], v[188:191], v[36:39]
	v_mfma_f32_16x16x32_bf16 v[32:35], v[228:231], v[188:191], v[32:35]
	s_waitcnt lgkmcnt(1)
	s_add_i32 m0, s17, 0xa810
	s_add_u32 s12, s42, 0x8000
	s_addc_u32 s13, s43, 0
	v_mfma_f32_16x16x32_bf16 v[28:31], v[216:219], v[192:195], v[28:31]
	v_mfma_f32_16x16x32_bf16 v[24:27], v[220:223], v[192:195], v[24:27]
	global_load_lds_dwordx4 v236, s[12:13]
	v_mfma_f32_16x16x32_bf16 v[20:23], v[224:227], v[192:195], v[20:23]
	v_mfma_f32_16x16x32_bf16 v[16:19], v[228:231], v[192:195], v[16:19]
	s_waitcnt lgkmcnt(0)
	s_add_i32 m0, s17, 0xac10
	s_add_u32 s12, s42, 0xc000
	s_addc_u32 s13, s43, 0
	v_mfma_f32_16x16x32_bf16 v[12:15], v[216:219], v[196:199], v[12:15]
	v_mfma_f32_16x16x32_bf16 v[8:11], v[220:223], v[196:199], v[8:11]
	global_load_lds_dwordx4 v237, s[12:13]
	v_mfma_f32_16x16x32_bf16 v[4:7], v[224:227], v[196:199], v[4:7]
	v_mfma_f32_16x16x32_bf16 v[0:3], v[228:231], v[196:199], v[0:3]
	s_waitcnt vmcnt(0)
	s_barrier
	s_lshl_b32 s19, s18, 8
	s_add_i32 s19, s19, 0x100
	s_min_u32 s19, s19, 0x780
	s_add_u32 s40, s8, s19
	s_addc_u32 s41, s9, 0
	s_add_u32 s42, s10, s19
	s_addc_u32 s43, s11, 0
	ds_read_b128 v[142:145], v234 offset:28672
	ds_read_b128 v[146:149], v234 offset:30720
	ds_read_b128 v[150:153], v234 offset:32768
	ds_read_b128 v[154:157], v234 offset:34816
	ds_read_b128 v[130:133], v232 offset:28672
	ds_read_b128 v[134:137], v232 offset:30720
	ds_read_b128 v[138:141], v232 offset:32768
	ds_read_b128 v[216:219], v235 offset:28672
	ds_read_b128 v[220:223], v235 offset:30720
	ds_read_b128 v[224:227], v235 offset:32768
	ds_read_b128 v[228:231], v235 offset:34816
	ds_read_b128 v[188:191], v233 offset:28672
	ds_read_b128 v[192:195], v233 offset:30720
	ds_read_b128 v[196:199], v233 offset:32768
	s_waitcnt lgkmcnt(9)
	s_add_i32 m0, s16, 0x10
	s_nop 0
	v_mfma_f32_16x16x32_bf16 v[72:75], v[142:145], v[130:133], v[72:75]
	global_load_lds_dwordx4 v238, s[40:41]
	s_add_i32 m0, s16, 0x410
	s_add_u32 s12, s40, 0x4000
	s_addc_u32 s13, s41, 0
	v_mfma_f32_16x16x32_bf16 v[40:43], v[146:149], v[130:133], v[40:43]
	global_load_lds_dwordx4 v239, s[12:13]
	v_mfma_f32_16x16x32_bf16 v[36:39], v[150:153], v[130:133], v[36:39]
	v_mfma_f32_16x16x32_bf16 v[32:35], v[154:157], v[130:133], v[32:35]
	s_waitcnt lgkmcnt(8)
	s_add_i32 m0, s16, 0x810
	s_add_u32 s12, s40, 0x8000
	s_addc_u32 s13, s41, 0
	v_mfma_f32_16x16x32_bf16 v[28:31], v[142:145], v[134:137], v[28:31]
	v_mfma_f32_16x16x32_bf16 v[24:27], v[146:149], v[134:137], v[24:27]
	global_load_lds_dwordx4 v238, s[12:13]
	v_mfma_f32_16x16x32_bf16 v[20:23], v[150:153], v[134:137], v[20:23]
	v_mfma_f32_16x16x32_bf16 v[16:19], v[154:157], v[134:137], v[16:19]
	s_waitcnt lgkmcnt(7)
	s_add_i32 m0, s17, 0x3010
	s_nop 0
	v_mfma_f32_16x16x32_bf16 v[12:15], v[142:145], v[138:141], v[12:15]
	v_mfma_f32_16x16x32_bf16 v[8:11], v[146:149], v[138:141], v[8:11]
	global_load_lds_dwordx4 v236, s[42:43]
	v_mfma_f32_16x16x32_bf16 v[4:7], v[150:153], v[138:141], v[4:7]
	v_mfma_f32_16x16x32_bf16 v[0:3], v[154:157], v[138:141], v[0:3]
	s_waitcnt lgkmcnt(2)
	s_add_i32 m0, s17, 0x3410
	s_add_u32 s12, s42, 0x4000
	s_addc_u32 s13, s43, 0
	v_mfma_f32_16x16x32_bf16 v[72:75], v[216:219], v[188:191], v[72:75]
	v_mfma_f32_16x16x32_bf16 v[40:43], v[220:223], v[188:191], v[40:43]
	global_load_lds_dwordx4 v237, s[12:13]
	v_mfma_f32_16x16x32_bf16 v[36:39], v[224:227], v[188:191], v[36:39]
	v_mfma_f32_16x16x32_bf16 v[32:35], v[228:231], v[188:191], v[32:35]
	s_waitcnt lgkmcnt(1)
	s_add_i32 m0, s17, 0x3810
	s_add_u32 s12, s42, 0x8000
	s_addc_u32 s13, s43, 0
	v_mfma_f32_16x16x32_bf16 v[28:31], v[216:219], v[192:195], v[28:31]
	v_mfma_f32_16x16x32_bf16 v[24:27], v[220:223], v[192:195], v[24:27]
	global_load_lds_dwordx4 v236, s[12:13]
	v_mfma_f32_16x16x32_bf16 v[20:23], v[224:227], v[192:195], v[20:23]
	v_mfma_f32_16x16x32_bf16 v[16:19], v[228:231], v[192:195], v[16:19]
	s_waitcnt lgkmcnt(0)
	s_add_i32 m0, s17, 0x3c10
	s_add_u32 s12, s42, 0xc000
	s_addc_u32 s13, s43, 0
	v_mfma_f32_16x16x32_bf16 v[12:15], v[216:219], v[196:199], v[12:15]
	v_mfma_f32_16x16x32_bf16 v[8:11], v[220:223], v[196:199], v[8:11]
	global_load_lds_dwordx4 v237, s[12:13]
	v_mfma_f32_16x16x32_bf16 v[4:7], v[224:227], v[196:199], v[4:7]
	v_mfma_f32_16x16x32_bf16 v[0:3], v[228:231], v[196:199], v[0:3]
	s_waitcnt vmcnt(0)
	s_barrier
	s_add_i32 s18, s18, 1
	s_cmp_eq_u32 s18, 8
	s_cbranch_scc0 .LBB1_90
	s_setprio 0
	s_waitcnt vmcnt(0)
	v_readlane_b32 s14, v242, 0
	s_add_i32 s15, s2, 1
	s_lshl_b32 s15, s15, 3
	s_and_b32 s24, s14, 7
	s_or_b32 s15, s15, s24
	s_mul_i32 s15, s15, s55
	s_lshr_b32 s14, s14, 3
	s_add_i32 s15, s15, s14
	s_cmp_lt_u32 s15, 0x580
	s_cselect_b32 s59, 1, 0
	s_cbranch_scc0 .Lg96pf_none_g2a
	s_lshr_b32 s14, s15, 6
	s_lshl_b32 s14, s14, 3
	s_and_b32 s24, s15, 7
	s_add_i32 s14, s14, s24
	s_mul_i32 s14, s14, 96
	s_sub_i32 s14, s14, s5
	s_bfe_u32 s24, s15, 0x30003
	s_lshl_b32 s24, s24, 7
	s_sub_i32 s24, s24, s4
	s_ashr_i32 s15, s14, 31
	s_lshl_b64 s[14:15], s[14:15], 11
	s_add_u32 s88, s8, s14
	s_addc_u32 s89, s9, s15
	s_ashr_i32 s25, s24, 31
	s_lshl_b64 s[24:25], s[24:25], 11
	s_add_u32 s90, s10, s24
	s_addc_u32 s91, s11, s25
	s_add_i32 m0, s16, 0x10
	s_nop 0
	global_load_lds_dwordx4 v238, s[88:89]
	s_add_i32 m0, s16, 0x410
	s_add_u32 s14, s88, 0x4000
	s_addc_u32 s15, s89, 0
	global_load_lds_dwordx4 v239, s[14:15]
	s_add_i32 m0, s16, 0x810
	s_add_u32 s14, s88, 0x8000
	s_addc_u32 s15, s89, 0
	global_load_lds_dwordx4 v238, s[14:15]
	s_add_i32 m0, s17, 0x3010
	s_nop 0
	global_load_lds_dwordx4 v236, s[90:91]
	s_add_i32 m0, s17, 0x3410
	s_add_u32 s14, s90, 0x4000
	s_addc_u32 s15, s91, 0
	global_load_lds_dwordx4 v237, s[14:15]
	s_add_i32 m0, s17, 0x3810
	s_add_u32 s14, s90, 0x8000
	s_addc_u32 s15, s91, 0
	global_load_lds_dwordx4 v236, s[14:15]
	s_add_i32 m0, s17, 0x3c10
	s_add_u32 s14, s90, 0xc000
	s_addc_u32 s15, s91, 0
	global_load_lds_dwordx4 v237, s[14:15]
.Lg96pf_none_g2a:
	v_readlane_b32 s6, v241, 34
	v_readlane_b32 s7, v241, 35
	s_load_dwordx2 s[12:13], s[0:1], 0x168
	v_and_b32_e32 v154, 15, v168
	v_lshrrev_b32_e32 v155, 4, v168
	v_lshrrev_b32_e32 v156, 7, v162
	v_bfe_u32 v157, v162, 6, 1
	v_mul_u32_u24_e32 v156, 48, v156
	v_add3_u32 v156, v156, v154, s5
	v_lshlrev_b32_e32 v157, 6, v157
	v_lshl_add_u32 v157, v155, 2, v157
	v_add_u32_e32 v157, s4, v157
	v_lshlrev_b32_e32 v53, 2, v157
	v_lshlrev_b32_e32 v158, 1, v157
	v_lshl_add_u32 v44, v156, 14, v158
	v_lshl_add_u32 v50, v156, 11, v158
	v_lshl_add_u32 v47, v156, 12, v53
	v_add_u32_e32 v156, 16, v156
	v_lshlrev_b32_e32 v158, 1, v157
	v_lshl_add_u32 v45, v156, 14, v158
	v_lshl_add_u32 v51, v156, 11, v158
	v_lshl_add_u32 v48, v156, 12, v53
	v_add_u32_e32 v156, 16, v156
	v_lshlrev_b32_e32 v158, 1, v157
	v_lshl_add_u32 v46, v156, 14, v158
	v_lshl_add_u32 v52, v156, 11, v158
	v_lshl_add_u32 v49, v156, 12, v53
	s_add_u32 s8, s6, 0
	s_addc_u32 s9, s7, 0
	s_add_u32 s10, s76, 0x3000
	s_addc_u32 s11, s77, 0
	global_load_dwordx4 v[54:57], v53, s[8:9] offset:0
	global_load_dwordx4 v[58:61], v53, s[8:9] offset:64
	global_load_dwordx4 v[62:65], v53, s[8:9] offset:128
	global_load_dwordx4 v[66:69], v53, s[8:9] offset:192
	global_load_dwordx2 v[188:189], v44, s[10:11] offset:0
	global_load_dwordx4 v[100:103], v47, s[72:73] offset:0
	global_load_dwordx2 v[190:191], v44, s[10:11] offset:32
	global_load_dwordx4 v[104:107], v47, s[72:73] offset:64
	global_load_dwordx2 v[192:193], v44, s[10:11] offset:64
	global_load_dwordx4 v[108:111], v47, s[72:73] offset:128
	global_load_dwordx2 v[194:195], v44, s[10:11] offset:96
	global_load_dwordx4 v[112:115], v47, s[72:73] offset:192
	global_load_dwordx2 v[196:197], v45, s[10:11] offset:0
	global_load_dwordx4 v[116:119], v48, s[72:73] offset:0
	global_load_dwordx2 v[198:199], v45, s[10:11] offset:32
	global_load_dwordx4 v[120:123], v48, s[72:73] offset:64
	global_load_dwordx2 v[200:201], v45, s[10:11] offset:64
	global_load_dwordx4 v[232:235], v48, s[72:73] offset:128
	global_load_dwordx2 v[202:203], v45, s[10:11] offset:96
	global_load_dwordx4 v[130:133], v48, s[72:73] offset:192
	global_load_dwordx2 v[204:205], v46, s[10:11] offset:0
	global_load_dwordx4 v[134:137], v49, s[72:73] offset:0
	global_load_dwordx2 v[206:207], v46, s[10:11] offset:32
	global_load_dwordx4 v[138:141], v49, s[72:73] offset:64
	global_load_dwordx2 v[208:209], v46, s[10:11] offset:64
	global_load_dwordx4 v[142:145], v49, s[72:73] offset:128
	global_load_dwordx2 v[210:211], v46, s[10:11] offset:96
	global_load_dwordx4 v[146:149], v49, s[72:73] offset:192
	s_add_i32 s2, s2, 1
	v_readlane_b32 s55, v241, 23
	s_waitcnt lgkmcnt(0)
	s_waitcnt vmcnt(22)
	v_lshlrev_b32_e32 v150, 16, v188
	v_and_b32_e32 v151, 0xffff0000, v188
	v_lshlrev_b32_e32 v152, 16, v189
	v_and_b32_e32 v153, 0xffff0000, v189
	v_pk_add_f32 v[150:151], v[54:55], v[150:151]
	v_pk_add_f32 v[152:153], v[56:57], v[152:153]
	s_nop 0
	v_mul_f32_e32 v150, 0xbfb8aa3b, v150
	v_mul_f32_e32 v151, 0xbfb8aa3b, v151
	v_mul_f32_e32 v152, 0xbfb8aa3b, v152
	v_mul_f32_e32 v153, 0xbfb8aa3b, v153
	v_exp_f32_e32 v150, v150
	v_exp_f32_e32 v151, v151
	v_exp_f32_e32 v152, v152
	v_exp_f32_e32 v153, v153
	v_add_f32_e32 v150, 1.0, v150
	v_add_f32_e32 v151, 1.0, v151
	v_add_f32_e32 v152, 1.0, v152
	v_add_f32_e32 v153, 1.0, v153
	v_rcp_f32_e32 v150, v150
	v_rcp_f32_e32 v151, v151
	v_rcp_f32_e32 v152, v152
	v_rcp_f32_e32 v153, v153
	v_pk_fma_f32 v[72:73], v[72:73], v[150:151], v[100:101]
	v_pk_fma_f32 v[74:75], v[74:75], v[152:153], v[102:103]
	s_nop 0
	v_cvt_pk_bf16_f32 v72, v72, v73
	v_cvt_pk_bf16_f32 v73, v74, v75
	global_store_dwordx2 v50, v[72:73], s[12:13] offset:0
	s_waitcnt vmcnt(20)
	v_lshlrev_b32_e32 v150, 16, v190
	v_and_b32_e32 v151, 0xffff0000, v190
	v_lshlrev_b32_e32 v152, 16, v191
	v_and_b32_e32 v153, 0xffff0000, v191
	v_pk_add_f32 v[150:151], v[58:59], v[150:151]
	v_pk_add_f32 v[152:153], v[60:61], v[152:153]
	s_nop 0
	v_mul_f32_e32 v150, 0xbfb8aa3b, v150
	v_mul_f32_e32 v151, 0xbfb8aa3b, v151
	v_mul_f32_e32 v152, 0xbfb8aa3b, v152
	v_mul_f32_e32 v153, 0xbfb8aa3b, v153
	v_exp_f32_e32 v150, v150
	v_exp_f32_e32 v151, v151
	v_exp_f32_e32 v152, v152
	v_exp_f32_e32 v153, v153
	v_add_f32_e32 v150, 1.0, v150
	v_add_f32_e32 v151, 1.0, v151
	v_add_f32_e32 v152, 1.0, v152
	v_add_f32_e32 v153, 1.0, v153
	v_rcp_f32_e32 v150, v150
	v_rcp_f32_e32 v151, v151
	v_rcp_f32_e32 v152, v152
	v_rcp_f32_e32 v153, v153
	v_pk_fma_f32 v[40:41], v[40:41], v[150:151], v[104:105]
	v_pk_fma_f32 v[42:43], v[42:43], v[152:153], v[106:107]
	s_nop 0
	v_cvt_pk_bf16_f32 v40, v40, v41
	v_cvt_pk_bf16_f32 v41, v42, v43
	global_store_dwordx2 v50, v[40:41], s[12:13] offset:32
	s_waitcnt vmcnt(18)
	v_lshlrev_b32_e32 v150, 16, v192
	v_and_b32_e32 v151, 0xffff0000, v192
	v_lshlrev_b32_e32 v152, 16, v193
	v_and_b32_e32 v153, 0xffff0000, v193
	v_pk_add_f32 v[150:151], v[62:63], v[150:151]
	v_pk_add_f32 v[152:153], v[64:65], v[152:153]
	s_nop 0
	v_mul_f32_e32 v150, 0xbfb8aa3b, v150
	v_mul_f32_e32 v151, 0xbfb8aa3b, v151
	v_mul_f32_e32 v152, 0xbfb8aa3b, v152
	v_mul_f32_e32 v153, 0xbfb8aa3b, v153
	v_exp_f32_e32 v150, v150
	v_exp_f32_e32 v151, v151
	v_exp_f32_e32 v152, v152
	v_exp_f32_e32 v153, v153
	v_add_f32_e32 v150, 1.0, v150
	v_add_f32_e32 v151, 1.0, v151
	v_add_f32_e32 v152, 1.0, v152
	v_add_f32_e32 v153, 1.0, v153
	v_rcp_f32_e32 v150, v150
	v_rcp_f32_e32 v151, v151
	v_rcp_f32_e32 v152, v152
	v_rcp_f32_e32 v153, v153
	v_pk_fma_f32 v[36:37], v[36:37], v[150:151], v[108:109]
	v_pk_fma_f32 v[38:39], v[38:39], v[152:153], v[110:111]
	s_nop 0
	v_cvt_pk_bf16_f32 v36, v36, v37
	v_cvt_pk_bf16_f32 v37, v38, v39
	global_store_dwordx2 v50, v[36:37], s[12:13] offset:64
	s_waitcnt vmcnt(16)
	v_lshlrev_b32_e32 v150, 16, v194
	v_and_b32_e32 v151, 0xffff0000, v194
	v_lshlrev_b32_e32 v152, 16, v195
	v_and_b32_e32 v153, 0xffff0000, v195
	v_pk_add_f32 v[150:151], v[66:67], v[150:151]
	v_pk_add_f32 v[152:153], v[68:69], v[152:153]
	s_nop 0
	v_mul_f32_e32 v150, 0xbfb8aa3b, v150
	v_mul_f32_e32 v151, 0xbfb8aa3b, v151
	v_mul_f32_e32 v152, 0xbfb8aa3b, v152
	v_mul_f32_e32 v153, 0xbfb8aa3b, v153
	v_exp_f32_e32 v150, v150
	v_exp_f32_e32 v151, v151
	v_exp_f32_e32 v152, v152
	v_exp_f32_e32 v153, v153
	v_add_f32_e32 v150, 1.0, v150
	v_add_f32_e32 v151, 1.0, v151
	v_add_f32_e32 v152, 1.0, v152
	v_add_f32_e32 v153, 1.0, v153
	v_rcp_f32_e32 v150, v150
	v_rcp_f32_e32 v151, v151
	v_rcp_f32_e32 v152, v152
	v_rcp_f32_e32 v153, v153
	v_pk_fma_f32 v[32:33], v[32:33], v[150:151], v[112:113]
	v_pk_fma_f32 v[34:35], v[34:35], v[152:153], v[114:115]
	s_nop 0
	v_cvt_pk_bf16_f32 v32, v32, v33
	v_cvt_pk_bf16_f32 v33, v34, v35
	global_store_dwordx2 v50, v[32:33], s[12:13] offset:96
	s_waitcnt vmcnt(14)
	v_lshlrev_b32_e32 v150, 16, v196
	v_and_b32_e32 v151, 0xffff0000, v196
	v_lshlrev_b32_e32 v152, 16, v197
	v_and_b32_e32 v153, 0xffff0000, v197
	v_pk_add_f32 v[150:151], v[54:55], v[150:151]
	v_pk_add_f32 v[152:153], v[56:57], v[152:153]
	s_nop 0
	v_mul_f32_e32 v150, 0xbfb8aa3b, v150
	v_mul_f32_e32 v151, 0xbfb8aa3b, v151
	v_mul_f32_e32 v152, 0xbfb8aa3b, v152
	v_mul_f32_e32 v153, 0xbfb8aa3b, v153
	v_exp_f32_e32 v150, v150
	v_exp_f32_e32 v151, v151
	v_exp_f32_e32 v152, v152
	v_exp_f32_e32 v153, v153
	v_add_f32_e32 v150, 1.0, v150
	v_add_f32_e32 v151, 1.0, v151
	v_add_f32_e32 v152, 1.0, v152
	v_add_f32_e32 v153, 1.0, v153
	v_rcp_f32_e32 v150, v150
	v_rcp_f32_e32 v151, v151
	v_rcp_f32_e32 v152, v152
	v_rcp_f32_e32 v153, v153
	v_pk_fma_f32 v[28:29], v[28:29], v[150:151], v[116:117]
	v_pk_fma_f32 v[30:31], v[30:31], v[152:153], v[118:119]
	s_nop 0
	v_cvt_pk_bf16_f32 v28, v28, v29
	v_cvt_pk_bf16_f32 v29, v30, v31
	global_store_dwordx2 v51, v[28:29], s[12:13] offset:0
	s_waitcnt vmcnt(12)
	v_lshlrev_b32_e32 v150, 16, v198
	v_and_b32_e32 v151, 0xffff0000, v198
	v_lshlrev_b32_e32 v152, 16, v199
	v_and_b32_e32 v153, 0xffff0000, v199
	v_pk_add_f32 v[150:151], v[58:59], v[150:151]
	v_pk_add_f32 v[152:153], v[60:61], v[152:153]
	s_nop 0
	v_mul_f32_e32 v150, 0xbfb8aa3b, v150
	v_mul_f32_e32 v151, 0xbfb8aa3b, v151
	v_mul_f32_e32 v152, 0xbfb8aa3b, v152
	v_mul_f32_e32 v153, 0xbfb8aa3b, v153
	v_exp_f32_e32 v150, v150
	v_exp_f32_e32 v151, v151
	v_exp_f32_e32 v152, v152
	v_exp_f32_e32 v153, v153
	v_add_f32_e32 v150, 1.0, v150
	v_add_f32_e32 v151, 1.0, v151
	v_add_f32_e32 v152, 1.0, v152
	v_add_f32_e32 v153, 1.0, v153
	v_rcp_f32_e32 v150, v150
	v_rcp_f32_e32 v151, v151
	v_rcp_f32_e32 v152, v152
	v_rcp_f32_e32 v153, v153
	v_pk_fma_f32 v[24:25], v[24:25], v[150:151], v[120:121]
	v_pk_fma_f32 v[26:27], v[26:27], v[152:153], v[122:123]
	s_nop 0
	v_cvt_pk_bf16_f32 v24, v24, v25
	v_cvt_pk_bf16_f32 v25, v26, v27
	global_store_dwordx2 v51, v[24:25], s[12:13] offset:32
	s_waitcnt vmcnt(10)
	v_lshlrev_b32_e32 v150, 16, v200
	v_and_b32_e32 v151, 0xffff0000, v200
	v_lshlrev_b32_e32 v152, 16, v201
	v_and_b32_e32 v153, 0xffff0000, v201
	v_pk_add_f32 v[150:151], v[62:63], v[150:151]
	v_pk_add_f32 v[152:153], v[64:65], v[152:153]
	s_nop 0
	v_mul_f32_e32 v150, 0xbfb8aa3b, v150
	v_mul_f32_e32 v151, 0xbfb8aa3b, v151
	v_mul_f32_e32 v152, 0xbfb8aa3b, v152
	v_mul_f32_e32 v153, 0xbfb8aa3b, v153
	v_exp_f32_e32 v150, v150
	v_exp_f32_e32 v151, v151
	v_exp_f32_e32 v152, v152
	v_exp_f32_e32 v153, v153
	v_add_f32_e32 v150, 1.0, v150
	v_add_f32_e32 v151, 1.0, v151
	v_add_f32_e32 v152, 1.0, v152
	v_add_f32_e32 v153, 1.0, v153
	v_rcp_f32_e32 v150, v150
	v_rcp_f32_e32 v151, v151
	v_rcp_f32_e32 v152, v152
	v_rcp_f32_e32 v153, v153
	v_pk_fma_f32 v[20:21], v[20:21], v[150:151], v[232:233]
	v_pk_fma_f32 v[22:23], v[22:23], v[152:153], v[234:235]
	s_nop 0
	v_cvt_pk_bf16_f32 v20, v20, v21
	v_cvt_pk_bf16_f32 v21, v22, v23
	global_store_dwordx2 v51, v[20:21], s[12:13] offset:64
	s_waitcnt vmcnt(8)
	v_lshlrev_b32_e32 v150, 16, v202
	v_and_b32_e32 v151, 0xffff0000, v202
	v_lshlrev_b32_e32 v152, 16, v203
	v_and_b32_e32 v153, 0xffff0000, v203
	v_pk_add_f32 v[150:151], v[66:67], v[150:151]
	v_pk_add_f32 v[152:153], v[68:69], v[152:153]
	s_nop 0
	v_mul_f32_e32 v150, 0xbfb8aa3b, v150
	v_mul_f32_e32 v151, 0xbfb8aa3b, v151
	v_mul_f32_e32 v152, 0xbfb8aa3b, v152
	v_mul_f32_e32 v153, 0xbfb8aa3b, v153
	v_exp_f32_e32 v150, v150
	v_exp_f32_e32 v151, v151
	v_exp_f32_e32 v152, v152
	v_exp_f32_e32 v153, v153
	v_add_f32_e32 v150, 1.0, v150
	v_add_f32_e32 v151, 1.0, v151
	v_add_f32_e32 v152, 1.0, v152
	v_add_f32_e32 v153, 1.0, v153
	v_rcp_f32_e32 v150, v150
	v_rcp_f32_e32 v151, v151
	v_rcp_f32_e32 v152, v152
	v_rcp_f32_e32 v153, v153
	v_pk_fma_f32 v[16:17], v[16:17], v[150:151], v[130:131]
	v_pk_fma_f32 v[18:19], v[18:19], v[152:153], v[132:133]
	s_nop 0
	v_cvt_pk_bf16_f32 v16, v16, v17
	v_cvt_pk_bf16_f32 v17, v18, v19
	global_store_dwordx2 v51, v[16:17], s[12:13] offset:96
	s_waitcnt vmcnt(6)
	v_lshlrev_b32_e32 v150, 16, v204
	v_and_b32_e32 v151, 0xffff0000, v204
	v_lshlrev_b32_e32 v152, 16, v205
	v_and_b32_e32 v153, 0xffff0000, v205
	v_pk_add_f32 v[150:151], v[54:55], v[150:151]
	v_pk_add_f32 v[152:153], v[56:57], v[152:153]
	s_nop 0
	v_mul_f32_e32 v150, 0xbfb8aa3b, v150
	v_mul_f32_e32 v151, 0xbfb8aa3b, v151
	v_mul_f32_e32 v152, 0xbfb8aa3b, v152
	v_mul_f32_e32 v153, 0xbfb8aa3b, v153
	v_exp_f32_e32 v150, v150
	v_exp_f32_e32 v151, v151
	v_exp_f32_e32 v152, v152
	v_exp_f32_e32 v153, v153
	v_add_f32_e32 v150, 1.0, v150
	v_add_f32_e32 v151, 1.0, v151
	v_add_f32_e32 v152, 1.0, v152
	v_add_f32_e32 v153, 1.0, v153
	v_rcp_f32_e32 v150, v150
	v_rcp_f32_e32 v151, v151
	v_rcp_f32_e32 v152, v152
	v_rcp_f32_e32 v153, v153
	v_pk_fma_f32 v[12:13], v[12:13], v[150:151], v[134:135]
	v_pk_fma_f32 v[14:15], v[14:15], v[152:153], v[136:137]
	s_nop 0
	v_cvt_pk_bf16_f32 v12, v12, v13
	v_cvt_pk_bf16_f32 v13, v14, v15
	global_store_dwordx2 v52, v[12:13], s[12:13] offset:0
	s_waitcnt vmcnt(4)
	v_lshlrev_b32_e32 v150, 16, v206
	v_and_b32_e32 v151, 0xffff0000, v206
	v_lshlrev_b32_e32 v152, 16, v207
	v_and_b32_e32 v153, 0xffff0000, v207
	v_pk_add_f32 v[150:151], v[58:59], v[150:151]
	v_pk_add_f32 v[152:153], v[60:61], v[152:153]
	s_nop 0
	v_mul_f32_e32 v150, 0xbfb8aa3b, v150
	v_mul_f32_e32 v151, 0xbfb8aa3b, v151
	v_mul_f32_e32 v152, 0xbfb8aa3b, v152
	v_mul_f32_e32 v153, 0xbfb8aa3b, v153
	v_exp_f32_e32 v150, v150
	v_exp_f32_e32 v151, v151
	v_exp_f32_e32 v152, v152
	v_exp_f32_e32 v153, v153
	v_add_f32_e32 v150, 1.0, v150
	v_add_f32_e32 v151, 1.0, v151
	v_add_f32_e32 v152, 1.0, v152
	v_add_f32_e32 v153, 1.0, v153
	v_rcp_f32_e32 v150, v150
	v_rcp_f32_e32 v151, v151
	v_rcp_f32_e32 v152, v152
	v_rcp_f32_e32 v153, v153
	v_pk_fma_f32 v[8:9], v[8:9], v[150:151], v[138:139]
	v_pk_fma_f32 v[10:11], v[10:11], v[152:153], v[140:141]
	s_nop 0
	v_cvt_pk_bf16_f32 v8, v8, v9
	v_cvt_pk_bf16_f32 v9, v10, v11
	global_store_dwordx2 v52, v[8:9], s[12:13] offset:32
	s_waitcnt vmcnt(2)
	v_lshlrev_b32_e32 v150, 16, v208
	v_and_b32_e32 v151, 0xffff0000, v208
	v_lshlrev_b32_e32 v152, 16, v209
	v_and_b32_e32 v153, 0xffff0000, v209
	v_pk_add_f32 v[150:151], v[62:63], v[150:151]
	v_pk_add_f32 v[152:153], v[64:65], v[152:153]
	s_nop 0
	v_mul_f32_e32 v150, 0xbfb8aa3b, v150
	v_mul_f32_e32 v151, 0xbfb8aa3b, v151
	v_mul_f32_e32 v152, 0xbfb8aa3b, v152
	v_mul_f32_e32 v153, 0xbfb8aa3b, v153
	v_exp_f32_e32 v150, v150
	v_exp_f32_e32 v151, v151
	v_exp_f32_e32 v152, v152
	v_exp_f32_e32 v153, v153
	v_add_f32_e32 v150, 1.0, v150
	v_add_f32_e32 v151, 1.0, v151
	v_add_f32_e32 v152, 1.0, v152
	v_add_f32_e32 v153, 1.0, v153
	v_rcp_f32_e32 v150, v150
	v_rcp_f32_e32 v151, v151
	v_rcp_f32_e32 v152, v152
	v_rcp_f32_e32 v153, v153
	v_pk_fma_f32 v[4:5], v[4:5], v[150:151], v[142:143]
	v_pk_fma_f32 v[6:7], v[6:7], v[152:153], v[144:145]
	s_nop 0
	v_cvt_pk_bf16_f32 v4, v4, v5
	v_cvt_pk_bf16_f32 v5, v6, v7
	global_store_dwordx2 v52, v[4:5], s[12:13] offset:64
	s_waitcnt vmcnt(0)
	v_lshlrev_b32_e32 v150, 16, v210
	v_and_b32_e32 v151, 0xffff0000, v210
	v_lshlrev_b32_e32 v152, 16, v211
	v_and_b32_e32 v153, 0xffff0000, v211
	v_pk_add_f32 v[150:151], v[66:67], v[150:151]
	v_pk_add_f32 v[152:153], v[68:69], v[152:153]
	s_nop 0
	v_mul_f32_e32 v150, 0xbfb8aa3b, v150
	v_mul_f32_e32 v151, 0xbfb8aa3b, v151
	v_mul_f32_e32 v152, 0xbfb8aa3b, v152
	v_mul_f32_e32 v153, 0xbfb8aa3b, v153
	v_exp_f32_e32 v150, v150
	v_exp_f32_e32 v151, v151
	v_exp_f32_e32 v152, v152
	v_exp_f32_e32 v153, v153
	v_add_f32_e32 v150, 1.0, v150
	v_add_f32_e32 v151, 1.0, v151
	v_add_f32_e32 v152, 1.0, v152
	v_add_f32_e32 v153, 1.0, v153
	v_rcp_f32_e32 v150, v150
	v_rcp_f32_e32 v151, v151
	v_rcp_f32_e32 v152, v152
	v_rcp_f32_e32 v153, v153
	v_pk_fma_f32 v[0:1], v[0:1], v[150:151], v[146:147]
	v_pk_fma_f32 v[2:3], v[2:3], v[152:153], v[148:149]
	s_nop 0
	v_cvt_pk_bf16_f32 v0, v0, v1
	v_cvt_pk_bf16_f32 v1, v2, v3
	global_store_dwordx2 v52, v[0:1], s[12:13] offset:96
	s_mov_b64 s[30:31], 0
	s_branch .LBB1_87
